# ERES0 loop (2 phases): same de-serialisation of the row / partial-sum load groups as ERES1
# baseline (speedup 1.0000x reference)
.LBB0_289:
	s_andn2_saveexec_b64 s[44:45], s[44:45]
	s_cbranch_execz .LBB0_293
	v_mov_b32_e32 v69, 0
	s_and_saveexec_b64 s[46:47], s[40:41]
	s_cbranch_execz .LBB0_292
	v_ashrrev_i32_e32 v59, 31, v58
	s_waitcnt lgkmcnt(0)
	v_lshlrev_b64 v[18:19], 6, v[58:59]
	v_lshl_add_u64 v[18:19], v[50:51], 0, v[18:19]
	global_load_dword v69, v[18:19], off

.LBB0_297:
	s_andn2_saveexec_b64 s[46:47], s[46:47]
	s_cbranch_execz .LBB0_301
	v_mov_b32_e32 v57, 0
	s_and_saveexec_b64 s[68:69], s[40:41]
	s_cbranch_execz .LBB0_300
	v_ashrrev_i32_e32 v19, 31, v18
	v_lshlrev_b64 v[20:21], 6, v[18:19]
	v_lshl_add_u64 v[20:21], v[50:51], 0, v[20:21]
	global_load_dword v57, v[20:21], off

.LBB0_306:
	s_nop 0
	s_nop 0
	s_mov_b64 s[26:27], 0
